# N1: g/scale/shift loads issued before the x waits; gate_prep row loop software-pipelined (next row prefetched during compute)
# baseline (speedup 1.0000x reference)
; __device__ __forceinline__ unsigned pk2(float lo, float hi) { f32x2n v = {lo, hi}; bf16x2n b = __builtin_convertvector(v, bf16x2n); return __builtin_bit_cast(unsigned, b); }
; #define p (kparams())
; __device__ __forceinline__ void norm_rows(const int wv_, KPR p, int l, int src_layer, const float* gvec, int part_shift, int part_scale, bool copy_ctx) {
;     ...
;     const float rstd = rsqrtf(wave_sum(ss) * (1.f / D) + 1e-6f);
;     if (copy_ctx && row_who(row) == 4) { float* xd = xrow_dst(p, row);
; #pragma unroll
;       for (int j = 0; j < 8; ++j) *(f32x4*)(xd + lane * 4 + 256 * j) = v[j]; }
; #pragma unroll
;     for (int j = 0; j < 8; ++j) { const int c = lane * 4 + 256 * j;
;       const f32x4 g = *(const f32x4*)(gvec + c), sh = *(const f32x4*)(mw + part_shift * 2048 + c), sc = *(const f32x4*)(mw + part_scale * 2048 + c);
;       f32x4 o;
; #pragma unroll
;       for (int e = 0; e < 4; ++e) o[e] = v[j][e] * rstd * g[e] * (1.f + sc[e]) + sh[e];
;       u32x2 w; w.x = pk2(o[0], o[1]); w.y = pk2(o[2], o[3]);
;       *(u32x2*)(H + (size_t)row * D + c) = w; }
.LBB0_131:
	s_or_b64 exec, exec, s[20:21]
	s_waitcnt lgkmcnt(0)
	v_add_f32_e32 v3, v53, v55
	v_fmamk_f32 v3, v3, 0x3a000000, v152
	v_mul_f32_e32 v37, 0x4b800000, v3
	v_cmp_gt_f32_e32 vcc, s96, v3
	v_ashrrev_i32_e32 v1, 31, v0
	v_lshlrev_b64 v[66:67], 12, v[0:1]
	v_cndmask_b32_e32 v3, v3, v37, vcc
	v_rsq_f32_e32 v3, v3
	v_lshl_add_u64 v[66:67], v[48:49], 0, v[66:67]
	v_mul_f32_e32 v1, 0x45800000, v3
	v_cndmask_b32_e32 v70, v3, v1, vcc
	v_pk_mul_f32 v[32:33], v[32:33], v[70:71] op_sel_hi:[1,0]
	v_pk_mul_f32 v[34:35], v[34:35], v[70:71] op_sel_hi:[1,0]
	v_pk_mul_f32 v[28:29], v[28:29], v[70:71] op_sel_hi:[1,0]
	v_pk_mul_f32 v[30:31], v[30:31], v[70:71] op_sel_hi:[1,0]
	v_pk_mul_f32 v[24:25], v[24:25], v[70:71] op_sel_hi:[1,0]
	v_pk_mul_f32 v[26:27], v[26:27], v[70:71] op_sel_hi:[1,0]
	v_pk_mul_f32 v[20:21], v[20:21], v[70:71] op_sel_hi:[1,0]
	v_pk_mul_f32 v[22:23], v[22:23], v[70:71] op_sel_hi:[1,0]
	v_pk_mul_f32 v[16:17], v[16:17], v[70:71] op_sel_hi:[1,0]
	v_pk_mul_f32 v[18:19], v[18:19], v[70:71] op_sel_hi:[1,0]
	v_pk_mul_f32 v[12:13], v[12:13], v[70:71] op_sel_hi:[1,0]
	v_pk_mul_f32 v[14:15], v[14:15], v[70:71] op_sel_hi:[1,0]
	v_pk_mul_f32 v[8:9], v[8:9], v[70:71] op_sel_hi:[1,0]
	v_pk_mul_f32 v[10:11], v[10:11], v[70:71] op_sel_hi:[1,0]
	v_pk_mul_f32 v[4:5], v[4:5], v[70:71] op_sel_hi:[1,0]
	v_pk_mul_f32 v[6:7], v[6:7], v[70:71] op_sel_hi:[1,0]
	v_add_u32_e32 v0, s73, v0
	v_cmp_lt_i32_e32 vcc, s35, v0
	s_or_b64 s[18:19], vcc, s[18:19]
	s_waitcnt vmcnt(21)
	v_pk_mul_f32 v[32:33], v[32:33], v[88:89]
	v_pk_mul_f32 v[34:35], v[34:35], v[90:91]
	v_pk_add_f32 v[228:229], v[120:121], 1.0 op_sel_hi:[1,0]
	v_pk_add_f32 v[230:231], v[122:123], 1.0 op_sel_hi:[1,0]
	v_pk_fma_f32 v[32:33], v[32:33], v[228:229], v[190:191]
	v_pk_fma_f32 v[34:35], v[34:35], v[230:231], v[192:193]
	v_cvt_pk_bf16_f32 v32, v32, v33
	v_cvt_pk_bf16_f32 v33, v34, v35
	global_store_dwordx2 v[66:67], v[32:33], off
	s_waitcnt vmcnt(19)
	v_pk_mul_f32 v[28:29], v[28:29], v[92:93]
	v_pk_mul_f32 v[30:31], v[30:31], v[94:95]
	v_pk_add_f32 v[228:229], v[124:125], 1.0 op_sel_hi:[1,0]
	v_pk_add_f32 v[230:231], v[126:127], 1.0 op_sel_hi:[1,0]
	v_pk_fma_f32 v[28:29], v[28:29], v[228:229], v[194:195]
	v_pk_fma_f32 v[30:31], v[30:31], v[230:231], v[196:197]
	v_cvt_pk_bf16_f32 v28, v28, v29
	v_cvt_pk_bf16_f32 v29, v30, v31
	global_store_dwordx2 v[66:67], v[28:29], off offset:512
	s_waitcnt vmcnt(17)
	v_pk_mul_f32 v[24:25], v[24:25], v[96:97]
	v_pk_mul_f32 v[26:27], v[26:27], v[98:99]
	v_pk_add_f32 v[228:229], v[128:129], 1.0 op_sel_hi:[1,0]
	v_pk_add_f32 v[230:231], v[130:131], 1.0 op_sel_hi:[1,0]
	v_pk_fma_f32 v[24:25], v[24:25], v[228:229], v[198:199]
	v_pk_fma_f32 v[26:27], v[26:27], v[230:231], v[200:201]
	v_cvt_pk_bf16_f32 v24, v24, v25
	v_cvt_pk_bf16_f32 v25, v26, v27
	global_store_dwordx2 v[66:67], v[24:25], off offset:1024
	s_waitcnt vmcnt(15)
	v_pk_mul_f32 v[20:21], v[20:21], v[100:101]
	v_pk_mul_f32 v[22:23], v[22:23], v[102:103]
	v_pk_add_f32 v[228:229], v[132:133], 1.0 op_sel_hi:[1,0]
	v_pk_add_f32 v[230:231], v[134:135], 1.0 op_sel_hi:[1,0]
	v_pk_fma_f32 v[20:21], v[20:21], v[228:229], v[202:203]
	v_pk_fma_f32 v[22:23], v[22:23], v[230:231], v[204:205]
	v_cvt_pk_bf16_f32 v20, v20, v21
	v_cvt_pk_bf16_f32 v21, v22, v23
	global_store_dwordx2 v[66:67], v[20:21], off offset:1536
	s_waitcnt vmcnt(13)
	v_pk_mul_f32 v[16:17], v[16:17], v[104:105]
	v_pk_mul_f32 v[18:19], v[18:19], v[106:107]
	v_pk_add_f32 v[228:229], v[136:137], 1.0 op_sel_hi:[1,0]
	v_pk_add_f32 v[230:231], v[138:139], 1.0 op_sel_hi:[1,0]
	v_pk_fma_f32 v[16:17], v[16:17], v[228:229], v[206:207]
	v_pk_fma_f32 v[18:19], v[18:19], v[230:231], v[208:209]
	v_cvt_pk_bf16_f32 v16, v16, v17
	v_cvt_pk_bf16_f32 v17, v18, v19
	global_store_dwordx2 v[66:67], v[16:17], off offset:2048
	s_waitcnt vmcnt(11)
	v_pk_mul_f32 v[12:13], v[12:13], v[108:109]
	v_pk_mul_f32 v[14:15], v[14:15], v[110:111]
	v_pk_add_f32 v[228:229], v[140:141], 1.0 op_sel_hi:[1,0]
	v_pk_add_f32 v[230:231], v[142:143], 1.0 op_sel_hi:[1,0]
	v_pk_fma_f32 v[12:13], v[12:13], v[228:229], v[210:211]
	v_pk_fma_f32 v[14:15], v[14:15], v[230:231], v[212:213]
	v_cvt_pk_bf16_f32 v12, v12, v13
	v_cvt_pk_bf16_f32 v13, v14, v15
	global_store_dwordx2 v[66:67], v[12:13], off offset:2560
	s_waitcnt vmcnt(9)
	v_pk_mul_f32 v[8:9], v[8:9], v[112:113]
	v_pk_mul_f32 v[10:11], v[10:11], v[114:115]
	v_pk_add_f32 v[228:229], v[144:145], 1.0 op_sel_hi:[1,0]
	v_pk_add_f32 v[230:231], v[146:147], 1.0 op_sel_hi:[1,0]
	v_pk_fma_f32 v[8:9], v[8:9], v[228:229], v[214:215]
	v_pk_fma_f32 v[10:11], v[10:11], v[230:231], v[216:217]
	v_cvt_pk_bf16_f32 v8, v8, v9
	v_cvt_pk_bf16_f32 v9, v10, v11
	global_store_dwordx2 v[66:67], v[8:9], off offset:3072
	s_waitcnt vmcnt(7)
	v_pk_mul_f32 v[4:5], v[4:5], v[116:117]
	v_pk_mul_f32 v[6:7], v[6:7], v[118:119]
	v_pk_add_f32 v[228:229], v[148:149], 1.0 op_sel_hi:[1,0]
	v_pk_add_f32 v[230:231], v[150:151], 1.0 op_sel_hi:[1,0]
	v_pk_fma_f32 v[4:5], v[4:5], v[228:229], v[218:219]
	v_pk_fma_f32 v[6:7], v[6:7], v[230:231], v[220:221]
	v_cvt_pk_bf16_f32 v4, v4, v5
	v_cvt_pk_bf16_f32 v5, v6, v7
	global_store_dwordx2 v[66:67], v[4:5], off offset:3584
	s_andn2_b64 exec, exec, s[18:19]
	s_cbranch_execz .LBB0_143

; #define p (kparams())
; __device__ __forceinline__ void norm_rows(const int wv_, KPR p, int l, int src_layer, const float* gvec, int part_shift, int part_scale, bool copy_ctx) {
;     ...
;     const float* x = xrow_ptr(p, src_layer, row);
;     const float* mw = modl + (size_t)row_who(row) * 12288;
;     f32x4 v[8]; float ss = 0.f;
; #pragma unroll
;     for (int j = 0; j < 8; ++j) { v[j] = *(const f32x4*)(x + lane * 4 + 256 * j); ss += v[j][0] * v[j][0] + v[j][1] * v[j][1] + v[j][2] * v[j][2] + v[j][3] * v[j][3]; }
;     const float rstd = rsqrtf(wave_sum(ss) * (1.f / D) + 1e-6f);
;     if (copy_ctx && row_who(row) == 4) { float* xd = xrow_dst(p, row);
; #pragma unroll
;       for (int j = 0; j < 8; ++j) *(f32x4*)(xd + lane * 4 + 256 * j) = v[j]; }
; #pragma unroll
;     for (int j = 0; j < 8; ++j) { const int c = lane * 4 + 256 * j;
;       const f32x4 g = *(const f32x4*)(gvec + c), sh = *(const f32x4*)(mw + part_shift * 2048 + c), sc = *(const f32x4*)(mw + part_scale * 2048 + c);
.Lnr_skip:
	v_mul_hi_i32_i24_e32 v65, 0xc000, v3
	v_mul_i32_i24_e32 v64, 0xc000, v3
	v_lshl_add_u64 v[64:65], s[14:15], 0, v[64:65]
	s_mov_b64 s[24:25], 0x2000
	v_lshl_add_u64 v[68:69], v[64:65], 0, s[24:25]
	v_mov_b32_e32 v67, v2
	v_lshl_add_u64 v[70:71], v[68:69], 0, v[66:67]
	v_lshl_add_u64 v[84:85], v[64:65], 0, v[66:67]
	s_mov_b64 s[24:25], 0x1000
	v_lshl_add_u64 v[222:223], v[38:39], 0, s[24:25]
	v_lshl_add_u64 v[224:225], v[70:71], 0, s[24:25]
	v_lshl_add_u64 v[226:227], v[84:85], 0, s[24:25]
	global_load_dwordx4 v[88:91], v[38:39], off
	global_load_dwordx4 v[120:123], v[70:71], off
	global_load_dwordx4 v[190:193], v[84:85], off
	global_load_dwordx4 v[92:95], v[38:39], off offset:1024
	global_load_dwordx4 v[124:127], v[70:71], off offset:1024
	global_load_dwordx4 v[194:197], v[84:85], off offset:1024
	global_load_dwordx4 v[96:99], v[38:39], off offset:2048
	global_load_dwordx4 v[128:131], v[70:71], off offset:2048
	global_load_dwordx4 v[198:201], v[84:85], off offset:2048
	global_load_dwordx4 v[100:103], v[38:39], off offset:3072
	global_load_dwordx4 v[132:135], v[70:71], off offset:3072
	global_load_dwordx4 v[202:205], v[84:85], off offset:3072
	global_load_dwordx4 v[104:107], v[222:223], off
	global_load_dwordx4 v[136:139], v[224:225], off
	global_load_dwordx4 v[206:209], v[226:227], off
	global_load_dwordx4 v[108:111], v[222:223], off offset:1024
	global_load_dwordx4 v[140:143], v[224:225], off offset:1024
	global_load_dwordx4 v[210:213], v[226:227], off offset:1024
	global_load_dwordx4 v[112:115], v[222:223], off offset:2048
	global_load_dwordx4 v[144:147], v[224:225], off offset:2048
	global_load_dwordx4 v[214:217], v[226:227], off offset:2048
	global_load_dwordx4 v[116:119], v[222:223], off offset:3072
	global_load_dwordx4 v[148:151], v[224:225], off offset:3072
	global_load_dwordx4 v[218:221], v[226:227], off offset:3072
	s_waitcnt vmcnt(30)
	v_mul_f32_e32 v53, v33, v33
	v_mul_f32_e32 v55, v29, v29
	s_waitcnt vmcnt(29)
	v_mul_f32_e32 v57, v25, v25
	v_fmac_f32_e32 v53, v32, v32
	v_fmac_f32_e32 v55, v28, v28
	s_waitcnt vmcnt(28)
	v_mul_f32_e32 v59, v21, v21
	v_fmac_f32_e32 v57, v24, v24
	v_fmac_f32_e32 v53, v34, v34
	v_fmac_f32_e32 v55, v30, v30
	v_fmac_f32_e32 v59, v20, v20
	v_fmac_f32_e32 v57, v26, v26
	v_fmac_f32_e32 v53, v35, v35
	v_fmac_f32_e32 v55, v31, v31
	v_fmac_f32_e32 v59, v22, v22
	v_fmac_f32_e32 v57, v27, v27
	v_add_f32_e32 v53, v53, v55
	v_fmac_f32_e32 v59, v23, v23
	v_add_f32_e32 v53, v53, v57
	v_add_f32_e32 v53, v53, v59
	v_cmp_eq_u32_e32 vcc, 4, v3
	s_and_b64 s[22:23], s[6:7], vcc
	s_waitcnt vmcnt(27)
	v_mov_b32_e32 v68, v17
	s_waitcnt vmcnt(26)
	v_mov_b32_e32 v69, v13
	v_mov_b32_e32 v64, v16
	v_mov_b32_e32 v65, v12
	v_pk_mul_f32 v[68:69], v[68:69], v[68:69]
	v_mov_b32_e32 v70, v18
	v_mov_b32_e32 v71, v14
	s_waitcnt vmcnt(25)
	v_mov_b32_e32 v76, v9
	s_waitcnt vmcnt(24)
	v_mov_b32_e32 v77, v5
	v_pk_fma_f32 v[64:65], v[64:65], v[64:65], v[68:69]
	v_mov_b32_e32 v72, v19
	v_mov_b32_e32 v73, v15
	v_mov_b32_e32 v74, v8
	v_mov_b32_e32 v75, v4
	v_pk_mul_f32 v[76:77], v[76:77], v[76:77]
	v_pk_fma_f32 v[64:65], v[70:71], v[70:71], v[64:65]
	v_mov_b32_e32 v78, v10
	v_mov_b32_e32 v79, v6
	v_pk_fma_f32 v[68:69], v[74:75], v[74:75], v[76:77]
	v_pk_fma_f32 v[64:65], v[72:73], v[72:73], v[64:65]
	v_mov_b32_e32 v80, v11
	v_mov_b32_e32 v81, v7
	v_pk_fma_f32 v[68:69], v[78:79], v[78:79], v[68:69]
	v_add_f32_e32 v53, v53, v64
	v_add_f32_e32 v53, v53, v65
	v_pk_fma_f32 v[64:65], v[80:81], v[80:81], v[68:69]
	s_nop 0
	v_add_f32_e32 v53, v53, v64
	v_add_f32_e32 v53, v53, v65
	ds_bpermute_b32 v55, v170, v53
	s_waitcnt lgkmcnt(0)
	v_add_f32_e32 v53, v53, v55
	ds_bpermute_b32 v55, v171, v53
	s_waitcnt lgkmcnt(0)
	v_add_f32_e32 v53, v53, v55
	ds_bpermute_b32 v55, v172, v53
	s_waitcnt lgkmcnt(0)
	v_add_f32_e32 v53, v53, v55
	ds_bpermute_b32 v55, v173, v53
	s_waitcnt lgkmcnt(0)
	v_add_f32_e32 v53, v53, v55
	ds_bpermute_b32 v55, v174, v53
	s_waitcnt lgkmcnt(0)
	v_add_f32_e32 v53, v53, v55
	ds_bpermute_b32 v55, v175, v53
	s_and_saveexec_b64 s[20:21], s[22:23]
	s_cbranch_execz .LBB0_131
	s_and_saveexec_b64 s[24:25], s[4:5]
	s_xor_b64 s[4:5], exec, s[24:25]
	s_load_dwordx2 s[22:23], s[10:11], 0x110
	v_lshl_add_u32 v1, v1, 12, v51
	v_add3_u32 v64, v0, v1, s89
	s_or_saveexec_b64 s[4:5], s[4:5]
	s_waitcnt lgkmcnt(0)
	v_mov_b64_e32 v[68:69], s[22:23]
	s_xor_b64 exec, exec, s[4:5]
	s_cbranch_execz .LBB0_130
	v_lshl_add_u32 v64, v1, 8, v37
	v_mov_b64_e32 v[68:69], s[16:17]
	s_branch .LBB0_130

; __device__ __forceinline__ float bf2f(bf16_t h) { return __uint_as_float((unsigned)h << 16); }
; __device__ __forceinline__ float lo16(unsigned u) { return __uint_as_float(u << 16); }
; __device__ __forceinline__ float hi16(unsigned u) { return __uint_as_float(u & 0xffff0000u); }
; __device__ __forceinline__ float sigm(float x) { return __builtin_amdgcn_rcpf(1.f + __expf(-x)); }
; #define p (kparams())
; __device__ __forceinline__ void gate_prep_rows(const int wv_, KPR p, int l, float* lsm  ) {
;     ...
;   float omlb[8];
;   { const float* gam = p->in[I_HGGAMMA];
; #pragma unroll
;     for (int e = 0; e < 8; ++e) { float lb = 0.f; if (l == 1) lb = __builtin_amdgcn_rcpf(1.f + __expf(gam[lane * 8 + e] - gam[C + lane * 8 + e])); omlb[e] = 1.f - lb; } }
;   __syncthreads();
;   const int d = lane >> 5, c0 = (lane & 31) * 8;
;   for (int row = blockIdx.x * 8 + wid; row < T; row += gridDim.x * 8) {
;     bf16_t* pr = PNG + (size_t)row * NNGP;
;     const u32x4 f0 = *(const u32x4*)(pr + O_HF + lane * 8), f1 = *(const u32x4*)(pr + O_HF + 512 + lane * 8);
;     const float mycode = bf2f(pr[O_GC + (lane & 31)]);
;     auto cvt = [](const u32x4 u) { h16x8 o; o[0] = (h16)lo16(u.x); o[1] = (h16)hi16(u.x); o[2] = (h16)lo16(u.y); o[3] = (h16)hi16(u.y); o[4] = (h16)lo16(u.z); o[5] = (h16)hi16(u.z); o[6] = (h16)lo16(u.w); o[7] = (h16)hi16(u.w); return o; };
;     auto kkf = [&](const u32x4 u) { float f[8] = {lo16(u.x), hi16(u.x), lo16(u.y), hi16(u.y), lo16(u.z), hi16(u.z), lo16(u.w), hi16(u.w)}; h16x8 o;
; #pragma unroll
;       for (int e = 0; e < 8; ++e) o[e] = (h16)(omlb[e] * sigm(-f[e])); return o; };
;     const h16x8 k0 = kkf(f0), k1 = kkf(f1);
.Lgp_lb_done:
.LBB0_504:
	v_ashrrev_i32_e32 v0, 6, v0
	s_waitcnt lgkmcnt(0)
	v_readlane_b32 s4, v242, 2
	s_barrier
	s_nop 0
	v_add_u32_e32 v0, s4, v0
	s_movk_i32 s4, 0x4400
	v_cmp_gt_i32_e32 vcc, s4, v0
	s_and_saveexec_b64 s[8:9], vcc
	s_cbranch_execz .LBB0_507
	v_and_b32_e32 v142, 31, v6
	v_sub_f32_e32 v160, 1.0, v1
	v_sub_f32_e32 v189, 1.0, v5
	v_lshl_add_u32 v1, v142, 5, 0
	v_lshrrev_b32_e32 v5, 5, v4
	v_sub_f32_e32 v161, 1.0, v8
	v_lshl_add_u32 v8, v5, 10, v1
	v_cmp_gt_u32_e64 s[4:5], 32, v4
	v_lshl_add_u32 v1, v5, 14, v1
	v_lshlrev_b32_e32 v4, 9, v5
	v_mov_b32_e32 v5, v2
	v_sub_f32_e32 v158, 1.0, v7
	v_lshl_add_u64 v[4:5], s[12:13], 0, v[4:5]
	v_lshlrev_b32_e32 v6, 4, v142
	v_mov_b32_e32 v7, v2
	v_lshl_add_u64 v[4:5], v[4:5], 0, v[6:7]
	s_mov_b64 s[6:7], 0x390e0000
	v_sub_f32_e32 v3, 1.0, v11
	v_sub_f32_e32 v157, 1.0, v12
	v_sub_f32_e32 v156, 1.0, v9
	v_sub_f32_e32 v159, 1.0, v10
	v_lshl_add_u64 v[162:163], v[4:5], 0, s[6:7]
	ds_read_b128 v[4:7], v8 offset:32768
	ds_read_b128 v[8:11], v8 offset:32784
	ds_read_b128 v[12:15], v1
	ds_read_b128 v[16:19], v1 offset:16
	ds_read_b128 v[20:23], v1 offset:1024
	ds_read_b128 v[24:27], v1 offset:1040
	ds_read_b128 v[28:31], v1 offset:2048
	ds_read_b128 v[32:35], v1 offset:2064
	ds_read_b128 v[36:39], v1 offset:3072
	ds_read_b128 v[40:43], v1 offset:3088
	ds_read_b128 v[44:47], v1 offset:4096
	ds_read_b128 v[48:51], v1 offset:4112
	ds_read_b128 v[52:55], v1 offset:5120
	ds_read_b128 v[56:59], v1 offset:5136
	ds_read_b128 v[60:63], v1 offset:6144
	ds_read_b128 v[64:67], v1 offset:6160
	ds_read_b128 v[68:71], v1 offset:7168
	ds_read_b128 v[72:75], v1 offset:7184
	ds_read_b128 v[76:79], v1 offset:8192
	ds_read_b128 v[80:83], v1 offset:8208
	ds_read_b128 v[84:87], v1 offset:9216
	ds_read_b128 v[88:91], v1 offset:9232
	ds_read_b128 v[92:95], v1 offset:10240
	ds_read_b128 v[96:99], v1 offset:10256
	ds_read_b128 v[100:103], v1 offset:11264
	ds_read_b128 v[104:107], v1 offset:11280
	ds_read_b128 v[108:111], v1 offset:12288
	ds_read_b128 v[112:115], v1 offset:12304
	ds_read_b128 v[116:119], v1 offset:13312
	ds_read_b128 v[120:123], v1 offset:13328
	ds_read_b128 v[124:127], v1 offset:14336
	ds_read_b128 v[128:131], v1 offset:14352
	ds_read_b128 v[132:135], v1 offset:15360
	ds_read_b128 v[136:139], v1 offset:15376
	s_add_u32 s10, s12, 0xa4e0000
	s_addc_u32 s11, s13, 0
	s_mov_b64 s[12:13], 0
	v_lshlrev_b32_e32 v164, 1, v140
	v_lshlrev_b32_e32 v166, 1, v142
	v_mov_b32_e32 v165, v2
	v_mov_b32_e32 v167, v2
	v_mov_b64_e32 v[226:227], s[10:11]
	v_mad_i64_i32 v[226:227], s[6:7], v0, s81, v[226:227]
	v_lshl_add_u64 v[224:225], v[226:227], 0, v[164:165]
	v_add_co_u32_e32 v224, vcc, 0x1000, v224
	s_nop 1
	v_addc_co_u32_e32 v225, vcc, 0, v225, vcc
	global_load_dwordx4 v[230:233], v[224:225], off offset:768
	global_load_dwordx4 v[234:237], v[224:225], off offset:1792
	v_lshl_add_u64 v[226:227], v[226:227], 0, v[166:167]
	v_add_co_u32_e32 v226, vcc, 0x2000, v226
	s_nop 1
	v_addc_co_u32_e32 v227, vcc, 0, v227, vcc
	global_load_ushort v238, v[226:227], off offset:2816
	s_waitcnt vmcnt(0)
.LBB0_506:
	v_mov_b64_e32 v[140:141], s[10:11]
	v_mad_i64_i32 v[148:149], s[6:7], v0, s81, v[140:141]
	v_mov_b32_e32 v165, v2
	v_lshl_add_u64 v[140:141], v[148:149], 0, v[164:165]
	v_add_co_u32_e32 v168, vcc, 0x1000, v140
	v_mov_b32_e32 v167, v2
	s_nop 0
	v_addc_co_u32_e32 v169, vcc, 0, v141, vcc
	v_lshl_add_u64 v[148:149], v[148:149], 0, v[166:167]
	v_add_co_u32_e32 v148, vcc, 0x2000, v148
	v_ashrrev_i32_e32 v1, 31, v0
	s_nop 0
	v_addc_co_u32_e32 v149, vcc, 0, v149, vcc
	s_waitcnt vmcnt(3)
	v_mov_b32_e32 v140, v230
	v_mov_b32_e32 v141, v231
	v_mov_b32_e32 v142, v232
	v_mov_b32_e32 v143, v233
	v_mov_b32_e32 v144, v234
	v_mov_b32_e32 v145, v235
	v_mov_b32_e32 v146, v236
	v_mov_b32_e32 v147, v237
	v_mov_b32_e32 v150, v238
	v_add_u32_e32 v228, s73, v0
	v_min_i32_e32 v228, s35, v228
	v_mov_b64_e32 v[226:227], s[10:11]
	v_mad_i64_i32 v[226:227], s[6:7], v228, s81, v[226:227]
	v_lshl_add_u64 v[224:225], v[226:227], 0, v[164:165]
	v_add_co_u32_e32 v224, vcc, 0x1000, v224
	s_nop 1
	v_addc_co_u32_e32 v225, vcc, 0, v225, vcc
	global_load_dwordx4 v[230:233], v[224:225], off offset:768
	global_load_dwordx4 v[234:237], v[224:225], off offset:1792
	v_lshl_add_u64 v[226:227], v[226:227], 0, v[166:167]
	v_add_co_u32_e32 v226, vcc, 0x2000, v226
	s_nop 1
	v_addc_co_u32_e32 v227, vcc, 0, v227, vcc
	global_load_ushort v238, v[226:227], off offset:2816
	v_lshlrev_b32_e32 v148, 16, v140
	v_and_b32_e32 v140, 0xffff0000, v140
	v_lshlrev_b32_e32 v149, 16, v141
	v_and_b32_e32 v141, 0xffff0000, v141
	v_lshlrev_b32_e32 v151, 16, v142
	v_lshlrev_b32_e32 v193, 16, v147
	v_and_b32_e32 v194, 0xffff0000, v147
	v_mul_f32_e32 v140, 0x3fb8aa3b, v140
	v_mul_f32_e32 v147, 0x3fb8aa3b, v149
	v_and_b32_e32 v142, 0xffff0000, v142
	v_lshlrev_b32_e32 v165, 16, v143
	v_and_b32_e32 v143, 0xffff0000, v143
	v_lshlrev_b32_e32 v191, 16, v146
	v_and_b32_e32 v192, 0xffff0000, v146
	v_mul_f32_e32 v146, 0x3fb8aa3b, v148
	v_mul_f32_e32 v141, 0x3fb8aa3b, v141
	v_mul_f32_e32 v148, 0x3fb8aa3b, v151
	v_exp_f32_e32 v140, v140
	v_exp_f32_e32 v147, v147
	v_mul_f32_e32 v142, 0x3fb8aa3b, v142
	v_mul_f32_e32 v143, 0x3fb8aa3b, v143
	v_exp_f32_e32 v141, v141
	v_exp_f32_e32 v148, v148
	v_exp_f32_e32 v142, v142
	v_exp_f32_e32 v143, v143
	v_lshlrev_b32_e32 v167, 16, v144
	v_and_b32_e32 v144, 0xffff0000, v144
	v_lshlrev_b32_e32 v190, 16, v145
	v_add_f32_e32 v140, 1.0, v140
	v_add_f32_e32 v147, 1.0, v147
	v_mul_f32_e32 v149, 0x3fb8aa3b, v165
	v_mul_f32_e32 v144, 0x3fb8aa3b, v144
	v_mul_f32_e32 v165, 0x3fb8aa3b, v190
	v_add_f32_e32 v190, 1.0, v141
	v_add_f32_e32 v148, 1.0, v148
	v_rcp_f32_e32 v140, v140
; __device__ __forceinline__ float lo16(unsigned u) { return __uint_as_float(u << 16); }
; __device__ __forceinline__ float hi16(unsigned u) { return __uint_as_float(u & 0xffff0000u); }
; __device__ __forceinline__ float sigm(float x) { return __builtin_amdgcn_rcpf(1.f + __expf(-x)); }
; __device__ __forceinline__ void gate_prep_rows(const int wv_, KPR p, int l, float* lsm  ) {
;     ...
;     auto kkf = [&](const u32x4 u) { float f[8] = {lo16(u.x), hi16(u.x), lo16(u.y), hi16(u.y), lo16(u.z), hi16(u.z), lo16(u.w), hi16(u.w)}; h16x8 o;
; #pragma unroll
;       for (int e = 0; e < 8; ++e) o[e] = (h16)(omlb[e] * sigm(-f[e])); return o; };
;     const h16x8 k0 = kkf(f0), k1 = kkf(f1);
;     float z[8];
; #pragma unroll
;     for (int e = 0; e < 8; ++e) z[e] = lsm[8192 + d * 256 + c0 + e];
; #pragma unroll
;     for (int r = 0; r < 16; ++r) { const float ca = __int_as_float(__builtin_amdgcn_readlane(__float_as_int(mycode), r)), cbv = __int_as_float(__builtin_amdgcn_readlane(__float_as_int(mycode), 16 + r));
;       const float cd = d ? cbv : ca; const float* wr_ = lsm + (d * 16 + r) * 256 + c0;
;       const f32x4 wa = *(const f32x4*)wr_, wb = *(const f32x4*)(wr_ + 4);
; #pragma unroll
;       for (int e = 0; e < 4; ++e) { z[e] += cd * wa[e]; z[4 + e] += cd * wb[e]; } }
	v_rcp_f32_e32 v141, v147
	v_and_b32_e32 v145, 0xffff0000, v145
	v_mul_f32_e32 v151, 0x3fb8aa3b, v167
	v_mul_f32_e32 v167, 0x3fb8aa3b, v191
	v_exp_f32_e32 v144, v144
	v_add_f32_e32 v191, 1.0, v142
	v_add_f32_e32 v195, 1.0, v143
	v_rcp_f32_e32 v142, v190
	v_rcp_f32_e32 v143, v148
	v_mul_f32_e32 v145, 0x3fb8aa3b, v145
	v_exp_f32_e32 v149, v149
	v_exp_f32_e32 v151, v151
	v_exp_f32_e32 v145, v145
	v_pk_mul_f32 v[140:141], v[160:161], v[140:141]
	v_add_f32_e32 v196, 1.0, v144
	v_rcp_f32_e32 v144, v191
	v_pk_mul_f32 v[142:143], v[158:159], v[142:143]
	v_cvt_pk_f16_f32 v191, v140, v141
	v_mul_f32_e32 v140, 0x3fb8aa3b, v192
	v_exp_f32_e32 v165, v165
	v_exp_f32_e32 v167, v167
	v_add_f32_e32 v149, 1.0, v149
	v_add_f32_e32 v151, 1.0, v151
	v_rcp_f32_e32 v190, v195
	v_cvt_pk_f16_f32 v195, v142, v143
	v_exp_f32_e32 v142, v140
	v_mul_f32_e32 v140, 0x3fb8aa3b, v193
	v_exp_f32_e32 v146, v146
	v_add_f32_e32 v197, 1.0, v145
	v_rcp_f32_e32 v145, v149
	v_rcp_f32_e32 v149, v151
	v_exp_f32_e32 v143, v140
	v_add_f32_e32 v165, 1.0, v165
	v_add_f32_e32 v167, 1.0, v167
	v_add_f32_e32 v146, 1.0, v146
	v_rcp_f32_e32 v147, v165
	v_rcp_f32_e32 v148, v197
	v_pk_mul_f32 v[144:145], v[156:157], v[144:145]
	v_fma_mixlo_f16 v165, v189, v149, 0
	v_rcp_f32_e32 v149, v167
	v_add_f32_e32 v142, 1.0, v142
	v_add_f32_e32 v143, 1.0, v143
	v_rcp_f32_e32 v198, v146
	v_rcp_f32_e32 v146, v196
	v_cvt_pk_f16_f32 v196, v144, v145
	v_rcp_f32_e32 v142, v142
	v_rcp_f32_e32 v143, v143
	v_mul_f32_e32 v144, 0x3fb8aa3b, v194
	v_exp_f32_e32 v144, v144
	v_pk_mul_f32 v[140:141], v[158:159], v[148:149]
	v_fma_mixlo_f16 v151, v189, v198, 0
	v_cvt_pk_f16_f32 v167, v140, v141
	v_pk_mul_f32 v[140:141], v[156:157], v[142:143]
	v_pk_mul_f32 v[146:147], v[160:161], v[146:147]
	v_cvt_pk_f16_f32 v140, v140, v141
	v_add_f32_e32 v141, 1.0, v144
	v_rcp_f32_e32 v192, v141
	v_lshlrev_b32_e32 v141, 16, v150
	v_pack_b32_f16 v144, v151, v191
	v_readlane_b32 s6, v141, 0
	v_readlane_b32 s7, v141, 16
	v_alignbit_b32 v150, v140, v167, 16
	v_lshrrev_b32_e32 v151, 16, v140
	v_mov_b32_e32 v140, s7
	v_mov_b32_e32 v142, s6
	v_cvt_pk_f16_f32 v197, v146, v147
	v_cndmask_b32_e64 v140, v140, v142, s[4:5]
	v_readlane_b32 s6, v141, 1
	v_readlane_b32 s7, v141, 17
	v_alignbit_b32 v145, v195, v191, 16
	v_alignbit_b32 v146, v196, v195, 16
	v_lshrrev_b32_e32 v147, 16, v196
	v_pack_b32_f16 v148, v165, v197
	v_alignbit_b32 v149, v167, v197, 16
	s_waitcnt lgkmcnt(14)
	v_fma_f32 v142, v12, v140, v4
	v_fma_f32 v143, v16, v140, v8
	v_fma_f32 v165, v13, v140, v5
	v_fma_f32 v167, v17, v140, v9
	v_fma_f32 v191, v14, v140, v6
	v_fma_f32 v193, v18, v140, v10
	v_fma_f32 v194, v15, v140, v7
	v_fma_f32 v195, v19, v140, v11
	v_mov_b32_e32 v140, s7
	v_mov_b32_e32 v196, s6
	v_cndmask_b32_e64 v140, v140, v196, s[4:5]
	v_readlane_b32 s6, v141, 2
	v_readlane_b32 s7, v141, 18
	v_fmac_f32_e32 v142, v20, v140
	v_fmac_f32_e32 v143, v24, v140
	v_fmac_f32_e32 v165, v21, v140
	v_fmac_f32_e32 v167, v25, v140
	v_fmac_f32_e32 v191, v22, v140
	v_fmac_f32_e32 v193, v26, v140
	v_fmac_f32_e32 v194, v23, v140
	v_fmac_f32_e32 v195, v27, v140
	v_mov_b32_e32 v140, s7
	v_mov_b32_e32 v196, s6
	v_cndmask_b32_e64 v140, v140, v196, s[4:5]
	v_readlane_b32 s6, v141, 3
	v_readlane_b32 s7, v141, 19
	v_fmac_f32_e32 v142, v28, v140
	v_fmac_f32_e32 v143, v32, v140
	v_fmac_f32_e32 v165, v29, v140
	v_fmac_f32_e32 v167, v33, v140
	v_fmac_f32_e32 v191, v30, v140
	v_fmac_f32_e32 v193, v34, v140
	v_fmac_f32_e32 v194, v31, v140
	v_fmac_f32_e32 v195, v35, v140
	v_mov_b32_e32 v140, s7
	v_mov_b32_e32 v196, s6
	v_cndmask_b32_e64 v140, v140, v196, s[4:5]
	v_readlane_b32 s6, v141, 4
	v_readlane_b32 s7, v141, 20
	v_fmac_f32_e32 v142, v36, v140
	v_fmac_f32_e32 v143, v40, v140
	v_fmac_f32_e32 v165, v37, v140
	v_fmac_f32_e32 v167, v41, v140
	v_fmac_f32_e32 v191, v38, v140
	v_fmac_f32_e32 v193, v42, v140
	v_fmac_f32_e32 v194, v39, v140
	v_fmac_f32_e32 v195, v43, v140
	v_mov_b32_e32 v140, s7
	v_mov_b32_e32 v196, s6
	v_cndmask_b32_e64 v140, v140, v196, s[4:5]
	v_readlane_b32 s6, v141, 5
	v_readlane_b32 s7, v141, 21
	v_fmac_f32_e32 v142, v44, v140
	v_fmac_f32_e32 v143, v48, v140
	v_fmac_f32_e32 v165, v45, v140
	v_fmac_f32_e32 v167, v49, v140
	v_fmac_f32_e32 v191, v46, v140
	v_fmac_f32_e32 v193, v50, v140
	v_fmac_f32_e32 v194, v47, v140
	v_fmac_f32_e32 v195, v51, v140
	v_mov_b32_e32 v140, s7
	v_mov_b32_e32 v196, s6
	v_cndmask_b32_e64 v140, v140, v196, s[4:5]
	v_readlane_b32 s6, v141, 6
	v_readlane_b32 s7, v141, 22
	v_fmac_f32_e32 v142, v52, v140
	v_fmac_f32_e32 v143, v56, v140
	v_fmac_f32_e32 v165, v53, v140
	v_fmac_f32_e32 v167, v57, v140
	v_fmac_f32_e32 v191, v54, v140
	v_fmac_f32_e32 v193, v58, v140
	v_fmac_f32_e32 v194, v55, v140
	v_fmac_f32_e32 v195, v59, v140
	v_mov_b32_e32 v140, s7
	v_mov_b32_e32 v196, s6
	v_cndmask_b32_e64 v140, v140, v196, s[4:5]
	v_readlane_b32 s6, v141, 7
	v_readlane_b32 s7, v141, 23
	v_fmac_f32_e32 v142, v60, v140
	v_fmac_f32_e32 v143, v64, v140
	v_fmac_f32_e32 v165, v61, v140
	v_fmac_f32_e32 v167, v65, v140
	v_fmac_f32_e32 v191, v62, v140
	v_fmac_f32_e32 v193, v66, v140
	v_fmac_f32_e32 v194, v63, v140
	v_fmac_f32_e32 v195, v67, v140
	v_mov_b32_e32 v140, s7
	v_mov_b32_e32 v196, s6
	v_cndmask_b32_e64 v140, v140, v196, s[4:5]
	v_readlane_b32 s6, v141, 8
	v_readlane_b32 s7, v141, 24
	v_fmac_f32_e32 v142, v68, v140
	v_fmac_f32_e32 v143, v72, v140
	v_fmac_f32_e32 v165, v69, v140
	v_fmac_f32_e32 v167, v73, v140
	v_fmac_f32_e32 v191, v70, v140
	v_fmac_f32_e32 v193, v74, v140
	v_fmac_f32_e32 v194, v71, v140
	v_fmac_f32_e32 v195, v75, v140
	v_mov_b32_e32 v140, s7
	v_mov_b32_e32 v196, s6
	v_cndmask_b32_e64 v140, v140, v196, s[4:5]
	v_readlane_b32 s6, v141, 9
	v_readlane_b32 s7, v141, 25
	v_fmac_f32_e32 v142, v76, v140
	v_fmac_f32_e32 v143, v80, v140
	v_fmac_f32_e32 v165, v77, v140
	v_fmac_f32_e32 v167, v81, v140
	v_fmac_f32_e32 v191, v78, v140
	v_fmac_f32_e32 v193, v82, v140
	v_fmac_f32_e32 v194, v79, v140
	v_fmac_f32_e32 v195, v83, v140
	v_mov_b32_e32 v140, s7
	v_mov_b32_e32 v196, s6
	v_cndmask_b32_e64 v140, v140, v196, s[4:5]
	v_readlane_b32 s6, v141, 10
	v_readlane_b32 s7, v141, 26
	s_waitcnt lgkmcnt(13)
; __device__ __forceinline__ void gate_prep_rows(const int wv_, KPR p, int l, float* lsm  ) {
;     ...
;     for (int r = 0; r < 16; ++r) { const float ca = __int_as_float(__builtin_amdgcn_readlane(__float_as_int(mycode), r)), cbv = __int_as_float(__builtin_amdgcn_readlane(__float_as_int(mycode), 16 + r));
;       const float cd = d ? cbv : ca; const float* wr_ = lsm + (d * 16 + r) * 256 + c0;
;       const f32x4 wa = *(const f32x4*)wr_, wb = *(const f32x4*)(wr_ + 4);
; #pragma unroll
;       for (int e = 0; e < 4; ++e) { z[e] += cd * wa[e]; z[4 + e] += cd * wb[e]; } }
	v_fmac_f32_e32 v142, v84, v140
	s_waitcnt lgkmcnt(12)
	v_fmac_f32_e32 v143, v88, v140
	v_fmac_f32_e32 v165, v85, v140
	v_fmac_f32_e32 v167, v89, v140
	v_fmac_f32_e32 v191, v86, v140
	v_fmac_f32_e32 v193, v90, v140
	v_fmac_f32_e32 v194, v87, v140
	v_fmac_f32_e32 v195, v91, v140
	v_mov_b32_e32 v140, s7
	v_mov_b32_e32 v196, s6
	v_cndmask_b32_e64 v140, v140, v196, s[4:5]
	v_readlane_b32 s6, v141, 11
	v_readlane_b32 s7, v141, 27
	s_waitcnt lgkmcnt(11)
	v_fmac_f32_e32 v142, v92, v140
	s_waitcnt lgkmcnt(10)
	v_fmac_f32_e32 v143, v96, v140
	v_fmac_f32_e32 v165, v93, v140
	v_fmac_f32_e32 v167, v97, v140
	v_fmac_f32_e32 v191, v94, v140
	v_fmac_f32_e32 v193, v98, v140
	v_fmac_f32_e32 v194, v95, v140
	v_fmac_f32_e32 v195, v99, v140
	v_mov_b32_e32 v140, s7
	v_mov_b32_e32 v196, s6
	v_cndmask_b32_e64 v140, v140, v196, s[4:5]
	v_readlane_b32 s6, v141, 12
	v_readlane_b32 s7, v141, 28
	s_waitcnt lgkmcnt(9)
	v_fmac_f32_e32 v142, v100, v140
	s_waitcnt lgkmcnt(8)
	v_fmac_f32_e32 v143, v104, v140
	v_fmac_f32_e32 v165, v101, v140
	v_fmac_f32_e32 v167, v105, v140
	v_fmac_f32_e32 v191, v102, v140
	v_fmac_f32_e32 v193, v106, v140
	v_fmac_f32_e32 v194, v103, v140
	v_fmac_f32_e32 v195, v107, v140
	v_mov_b32_e32 v140, s7
	v_mov_b32_e32 v196, s6
	v_cndmask_b32_e64 v140, v140, v196, s[4:5]
	v_readlane_b32 s6, v141, 13
	v_readlane_b32 s7, v141, 29
	s_waitcnt lgkmcnt(7)
	v_fmac_f32_e32 v142, v108, v140
	s_waitcnt lgkmcnt(6)
	v_fmac_f32_e32 v143, v112, v140
	v_fmac_f32_e32 v165, v109, v140
	v_fmac_f32_e32 v167, v113, v140
	v_fmac_f32_e32 v191, v110, v140
	v_fmac_f32_e32 v193, v114, v140
	v_fmac_f32_e32 v194, v111, v140
	v_fmac_f32_e32 v195, v115, v140
	v_mov_b32_e32 v140, s7
	v_mov_b32_e32 v196, s6
	v_cndmask_b32_e64 v140, v140, v196, s[4:5]
	v_readlane_b32 s6, v141, 14
	v_readlane_b32 s7, v141, 30
	s_waitcnt lgkmcnt(5)
	v_fmac_f32_e32 v142, v116, v140
	s_waitcnt lgkmcnt(4)
	v_fmac_f32_e32 v143, v120, v140
	v_fmac_f32_e32 v165, v117, v140
	v_fmac_f32_e32 v167, v121, v140
	v_fmac_f32_e32 v191, v118, v140
	v_fmac_f32_e32 v193, v122, v140
	v_fmac_f32_e32 v194, v119, v140
	v_fmac_f32_e32 v195, v123, v140
	v_mov_b32_e32 v140, s7
	v_mov_b32_e32 v196, s6
	v_cndmask_b32_e64 v140, v140, v196, s[4:5]
	v_readlane_b32 s6, v141, 15
	v_readlane_b32 s7, v141, 31
	s_waitcnt lgkmcnt(3)
	v_fmac_f32_e32 v142, v124, v140
	s_waitcnt lgkmcnt(2)
	v_fmac_f32_e32 v143, v128, v140
	v_fmac_f32_e32 v165, v125, v140
	v_fmac_f32_e32 v167, v129, v140
	v_fmac_f32_e32 v191, v126, v140
	v_fmac_f32_e32 v193, v130, v140
	v_fmac_f32_e32 v194, v127, v140
	v_fmac_f32_e32 v195, v131, v140
	v_mov_b32_e32 v140, s7
	v_mov_b32_e32 v141, s6
	v_cndmask_b32_e64 v140, v140, v141, s[4:5]
	s_waitcnt lgkmcnt(1)
	v_fmac_f32_e32 v142, v132, v140
	v_mul_f32_e32 v141, 0xbfb8aa3b, v142
	v_exp_f32_e32 v141, v141
	v_fmac_f32_e32 v165, v133, v140
	v_fmac_f32_e32 v191, v134, v140
	s_waitcnt lgkmcnt(0)
; __device__ __forceinline__ void gate_prep_rows(const int wv_, KPR p, int l, float* lsm  ) {
;     ...
;     h16x8 go;
; #pragma unroll
;     for (int e = 0; e < 8; ++e) { const float ls = -__logf(1.f + __expf(-z[e])); go[e] = (h16)(1.f - __expf(ls * (1.f / 16.f))); }
;     *(h16x8*)(pr + O_HF + lane * 8) = k0; *(h16x8*)(pr + O_HF + 512 + lane * 8) = k1;
;     *(h16x8*)(GLAU + (size_t)row * 512 + d * 256 + c0) = go;
	v_fmac_f32_e32 v143, v136, v140
	v_add_f32_e32 v141, 1.0, v141
	v_cmp_gt_f32_e32 vcc, s96, v141
	v_fmac_f32_e32 v167, v137, v140
	v_fmac_f32_e32 v193, v138, v140
	v_cndmask_b32_e64 v142, 0, 32, vcc
	v_ldexp_f32 v141, v141, v142
	v_log_f32_e32 v141, v141
	v_fmac_f32_e32 v194, v135, v140
	v_fmac_f32_e32 v195, v139, v140
	v_fma_mixhi_f16 v147, v3, v190, 0
	v_mul_f32_e32 v142, 0x3f317217, v141
	v_fma_f32 v142, v141, s37, -v142
	v_fmac_f32_e32 v142, 0x3377d1cf, v141
	v_fmac_f32_e32 v142, 0x3f317217, v141
	v_cmp_lt_f32_e64 s[6:7], |v141|, s38
	v_mul_f32_e32 v143, 0xbfb8aa3b, v143
	v_exp_f32_e32 v143, v143
	v_cndmask_b32_e64 v141, v141, v142, s[6:7]
	v_cndmask_b32_e32 v142, 0, v181, vcc
	v_sub_f32_e32 v141, v141, v142
	v_mul_f32_e32 v142, 0xbfb8aa3b, v165
	v_exp_f32_e32 v142, v142
	v_mul_f32_e32 v141, 0xbd800000, v141
	v_mul_f32_e32 v141, 0x3fb8aa3b, v141
	v_exp_f32_e32 v141, v141
	v_add_f32_e32 v142, 1.0, v142
	v_cmp_gt_f32_e32 vcc, s96, v142
	v_fma_mixhi_f16 v151, v3, v192, 0
	global_store_dwordx4 v[168:169], v[144:147], off offset:768
	global_store_dwordx4 v[168:169], v[148:151], off offset:1792
	v_cndmask_b32_e64 v165, 0, 32, vcc
	v_ldexp_f32 v142, v142, v165
	v_log_f32_e32 v142, v142
	v_sub_f32_e32 v165, 1.0, v141
	v_mul_f32_e32 v141, 0xbfb8aa3b, v191
	v_exp_f32_e32 v141, v141
	v_mul_f32_e32 v140, 0x3f317217, v142
	v_fma_f32 v140, v142, s37, -v140
	v_fmac_f32_e32 v140, 0x3377d1cf, v142
	v_fmac_f32_e32 v140, 0x3f317217, v142
	v_cmp_lt_f32_e64 s[6:7], |v142|, s38
	v_add_f32_e32 v141, 1.0, v141
	v_cvt_f16_f32_e32 v165, v165
	v_cndmask_b32_e64 v140, v142, v140, s[6:7]
	v_cndmask_b32_e32 v142, 0, v181, vcc
	v_cmp_gt_f32_e32 vcc, s96, v141
	v_sub_f32_e32 v140, v140, v142
	v_mul_f32_e32 v140, 0xbd800000, v140
	v_cndmask_b32_e64 v142, 0, 32, vcc
	v_ldexp_f32 v141, v141, v142
	v_log_f32_e32 v141, v141
	v_mul_f32_e32 v140, 0x3fb8aa3b, v140
	v_exp_f32_e32 v140, v140
	v_lshlrev_b64 v[144:145], 10, v[0:1]
	v_mul_f32_e32 v142, 0x3f317217, v141
	v_fma_f32 v142, v141, s37, -v142
	v_fmac_f32_e32 v142, 0x3377d1cf, v141
	v_fmac_f32_e32 v142, 0x3f317217, v141
	v_cmp_lt_f32_e64 s[6:7], |v141|, s38
	v_add_u32_e32 v0, s73, v0
	v_lshl_add_u64 v[144:145], v[162:163], 0, v[144:145]
	v_cndmask_b32_e64 v141, v141, v142, s[6:7]
	v_cndmask_b32_e32 v142, 0, v181, vcc
	v_sub_f32_e32 v141, v141, v142
	v_mul_f32_e32 v142, 0xbfb8aa3b, v194
	v_exp_f32_e32 v142, v142
	v_mul_f32_e32 v141, 0xbd800000, v141
	v_mul_f32_e32 v141, 0x3fb8aa3b, v141
	v_exp_f32_e32 v141, v141
	v_add_f32_e32 v142, 1.0, v142
	v_cmp_gt_f32_e32 vcc, s96, v142
	v_pk_add_f32 v[140:141], v[140:141], 1.0 op_sel_hi:[1,0] neg_lo:[1,0] neg_hi:[1,0]
	s_nop 0
	v_cndmask_b32_e64 v190, 0, 32, vcc
	v_ldexp_f32 v142, v142, v190
	v_log_f32_e32 v142, v142
	v_cvt_pk_f16_f32 v141, v140, v141
	v_mul_f32_e32 v190, 0xbfb8aa3b, v195
	v_exp_f32_e32 v190, v190
	v_mul_f32_e32 v140, 0x3f317217, v142
	v_fma_f32 v140, v142, s37, -v140
	v_fmac_f32_e32 v140, 0x3377d1cf, v142
	v_fmac_f32_e32 v140, 0x3f317217, v142
	v_cmp_lt_f32_e64 s[6:7], |v142|, s38
	s_nop 1
	v_cndmask_b32_e64 v140, v142, v140, s[6:7]
	v_cndmask_b32_e32 v142, 0, v181, vcc
	v_sub_f32_e32 v140, v140, v142
	v_add_f32_e32 v142, 1.0, v143
	v_cmp_gt_f32_e32 vcc, s96, v142
	v_mul_f32_e32 v140, 0xbd800000, v140
	v_mul_f32_e32 v140, 0x3fb8aa3b, v140
	v_cndmask_b32_e64 v143, 0, 32, vcc
	v_ldexp_f32 v142, v142, v143
	v_log_f32_e32 v143, v142
	v_exp_f32_e32 v142, v140
	v_mul_f32_e32 v140, 0x3f317217, v143
	v_fma_f32 v140, v143, s37, -v140
	v_fmac_f32_e32 v140, 0x3377d1cf, v143
	v_fmac_f32_e32 v140, 0x3f317217, v143
	v_cmp_lt_f32_e64 s[6:7], |v143|, s38
	s_nop 1
	v_cndmask_b32_e64 v140, v143, v140, s[6:7]
	v_cndmask_b32_e32 v143, 0, v181, vcc
	v_sub_f32_e32 v140, v140, v143
	v_mul_f32_e32 v143, 0xbfb8aa3b, v167
	v_exp_f32_e32 v167, v143
	v_mul_f32_e32 v140, 0xbd800000, v140
	v_mul_f32_e32 v140, 0x3fb8aa3b, v140
	v_exp_f32_e32 v143, v140
	v_add_f32_e32 v140, 1.0, v167
	v_cmp_gt_f32_e32 vcc, s96, v140
	v_pk_add_f32 v[142:143], v[142:143], 1.0 op_sel_hi:[1,0] neg_lo:[1,0] neg_hi:[1,0]
	s_nop 0
	v_cndmask_b32_e64 v167, 0, 32, vcc
	v_ldexp_f32 v140, v140, v167
	v_log_f32_e32 v167, v140
	v_pack_b32_f16 v140, v165, v141
	v_cvt_pk_f16_f32 v165, v142, v143
	v_mul_f32_e32 v143, 0xbfb8aa3b, v193
	v_exp_f32_e32 v143, v143
	v_mul_f32_e32 v142, 0x3f317217, v167
	v_fma_f32 v142, v167, s37, -v142
	v_fmac_f32_e32 v142, 0x3377d1cf, v167
	v_fmac_f32_e32 v142, 0x3f317217, v167
	v_cmp_lt_f32_e64 s[6:7], |v167|, s38
	v_add_f32_e32 v143, 1.0, v143
	v_alignbit_b32 v141, v165, v141, 16
	v_cndmask_b32_e64 v142, v167, v142, s[6:7]
	v_cndmask_b32_e32 v167, 0, v181, vcc
	v_cmp_gt_f32_e32 vcc, s96, v143
	v_sub_f32_e32 v142, v142, v167
	v_mul_f32_e32 v142, 0xbd800000, v142
	v_cndmask_b32_e64 v167, 0, 32, vcc
	v_ldexp_f32 v143, v143, v167
	v_log_f32_e32 v143, v143
	v_mul_f32_e32 v142, 0x3fb8aa3b, v142
	v_exp_f32_e32 v142, v142
	v_mul_f32_e32 v167, 0x3f317217, v143
	v_fma_f32 v167, v143, s37, -v167
	v_fmac_f32_e32 v167, 0x3377d1cf, v143
	v_fmac_f32_e32 v167, 0x3f317217, v143
	v_cmp_lt_f32_e64 s[6:7], |v143|, s38
	s_nop 1
	v_cndmask_b32_e64 v143, v143, v167, s[6:7]
	v_add_f32_e32 v167, 1.0, v190
	v_cmp_gt_f32_e64 s[6:7], s96, v167
	s_nop 1
	v_cndmask_b32_e64 v190, 0, 32, s[6:7]
	v_ldexp_f32 v167, v167, v190
	v_log_f32_e32 v167, v167
	v_cndmask_b32_e32 v190, 0, v181, vcc
	v_sub_f32_e32 v143, v143, v190
	v_mul_f32_e32 v143, 0xbd800000, v143
	v_mul_f32_e32 v190, 0x3f317217, v167
	v_fma_f32 v190, v167, s37, -v190
	v_fmac_f32_e32 v190, 0x3377d1cf, v167
	v_fmac_f32_e32 v190, 0x3f317217, v167
	v_cmp_lt_f32_e64 vcc, |v167|, s38
	v_mul_f32_e32 v143, 0x3fb8aa3b, v143
	v_exp_f32_e32 v143, v143
	v_cndmask_b32_e32 v167, v167, v190, vcc
	v_cndmask_b32_e64 v190, 0, v181, s[6:7]
	v_sub_f32_e32 v167, v167, v190
	v_mul_f32_e32 v167, 0xbd800000, v167
	v_mul_f32_e32 v167, 0x3fb8aa3b, v167
	v_exp_f32_e32 v167, v167
	v_pk_add_f32 v[142:143], v[142:143], 1.0 op_sel_hi:[1,0] neg_lo:[1,0] neg_hi:[1,0]
	v_cmp_lt_i32_e32 vcc, s35, v0
	v_cvt_pk_f16_f32 v143, v142, v143
	v_sub_f32_e32 v167, 1.0, v167
	v_cvt_f16_f32_e32 v167, v167
	v_alignbit_b32 v142, v143, v165, 16
	s_or_b64 s[12:13], vcc, s[12:13]
	v_alignbit_b32 v143, v167, v143, 16
	global_store_dwordx4 v[144:145], v[140:143], off
	s_andn2_b64 exec, exec, s[12:13]
	s_cbranch_execnz .LBB0_506
